# v043 + P9 K-loop LDS-DMA: 6 of the 64-bit VALU address adds folded into the saddr form of global_load_lds
# speedup vs baseline: 1.0013x; 1.0013x over previous
; #define PG8_STAGE(bufoff, gbase, voff) do { _Pragma("unroll") for (int _i = 0; _i < 2; ++_i) \
;         __builtin_amdgcn_global_load_lds((const unsigned*)((const char*)(gbase) + (voff)[_i]), (LAS unsigned*)(lds + (bufoff) + ldsw + _i * 8192), 16, 0, 0); } while (0)
; #define PG8_LDA(dst, b, h) do { _Pragma("unroll") for (int m = 0; m < 4; ++m) _Pragma("unroll") for (int k = 0; k < 2; ++k) dst[m][k] = *(const LAS bf16x8*)(lds + PG8_SA(b, h) + aoff + m * 2048 + k * 1024); } while (0)
; #define PG8_LDB(dst, b, h) do { _Pragma("unroll") for (int n = 0; n < 2; ++n) _Pragma("unroll") for (int k = 0; k < 2; ++k) dst[n][k] = *(const LAS bf16x8*)(lds + PG8_SB(b, h) + boff + n * 2048 + k * 1024); } while (0)
; #define PG8_MMA(ai, bj, At, Bt) do { __builtin_amdgcn_s_setprio(1); _Pragma("unroll") for (int m = 0; m < 4; ++m) _Pragma("unroll") for (int n = 0; n < 2; ++n) _Pragma("unroll") for (int k = 0; k < 2; ++k) \
;         acc[ai][bj][m][n] = __builtin_amdgcn_mfma_f32_16x16x32_bf16(Bt[n][k], At[m][k], acc[ai][bj][m][n], 0, 0, 0); __builtin_amdgcn_s_setprio(0); } while (0)
; #define PG8_WAIT_V(n) asm volatile("s_waitcnt vmcnt(" #n ")" ::: "memory")
; #define PG8_WAIT_L(n) asm volatile("s_waitcnt lgkmcnt(" #n ")" ::: "memory")
; template <class Epi, class Sched, bool APERM = false, bool HALFN = false>
; __device__ __forceinline__ void gemm_phase(LAS unsigned char* lds, const int tid_in, const int K, const Sched& S, const Epi& E) {
;     ...
;     for (;;) {
;         const bool has_next = S.next(ui + 1, nxt);
;         const char* nA = has_next ? nxt.A : cA; const char* nB = has_next ? nxt.B : cB;
;         for (int t = 0; t < nt; t += 2) {
;             const bool last = (t == nt - 2);
;             const char* a1 = cA + (size_t)(t + 1) * kstep;
;             const char* a2 = last ? nA : cA + (size_t)(t + 2) * kstep; const char* b2 = last ? nB : cB + (size_t)(t + 2) * kstep;
;             const char* a3 = a2 + kstep; const char* b3 = b2 + kstep;
;             PG8_LDB(B0, 0, 0); PG8_LDB(B1, 0, 1); PG8_SCHED; PG8_LDA(At, 0, 0); PG8_STAGE(PG8_SA(1, 1), a1 + hstepA, voffA);
;             PG8_WAIT_V(8); PG8_WAIT_L(0); PG8_BAR; PG8_MMA(0, 0, At, B0); if constexpr (!HALFN) PG8_MMA(0, 1, At, B1); PG8_BAR; PG8_SCHED;
;             PG8_LDA(At, 0, 1); PG8_STAGE(PG8_SB(0, 0), b2, voffB); PG8_STAGE(PG8_SB(0, 1), b2 + hstep, voffB); PG8_STAGE(PG8_SA(0, 0), a2, voffA);
.Lpf_done:
.LBB0_902:
	s_add_u32 s4, s0, 0x100
	s_addc_u32 s5, s1, 0
	s_add_i32 s14, 0, 0x10000
	s_cmp_eq_u32 s13, 28
	s_cselect_b32 s9, s23, s5
	s_cselect_b32 s8, s22, s4
	v_add_u32_e32 v52, s14, v202
	s_cselect_b32 s7, s25, s12
	s_cselect_b32 s6, s24, s11
	s_add_i32 s15, 0, 0x14000
	ds_read_b128 v[62:65], v52
	ds_read_b128 v[128:131], v52 offset:1024
	ds_read_b128 v[132:135], v52 offset:2048
	ds_read_b128 v[136:139], v52 offset:3072
	v_add_u32_e32 v52, s15, v202
	ds_read_b128 v[140:143], v52
	ds_read_b128 v[152:155], v52 offset:1024
	ds_read_b128 v[156:159], v52 offset:2048
	ds_read_b128 v[160:163], v52 offset:3072
	s_add_i32 m0, s57, 0xc000
	ds_read_b128 v[164:167], v243
	ds_read_b128 v[168:171], v243 offset:1024
	ds_read_b128 v[172:175], v243 offset:2048
	ds_read_b128 v[176:179], v243 offset:3072
	ds_read_b128 v[180:183], v243 offset:4096
	ds_read_b128 v[184:187], v243 offset:5120
	ds_read_b128 v[188:191], v243 offset:6144
	ds_read_b128 v[192:195], v243 offset:7168
	global_load_lds_dwordx4 v214, s[0:1]
	s_add_i32 m0, s57, 0xe000
	s_nop 0
	global_load_lds_dwordx4 v212, s[0:1]
	s_waitcnt vmcnt(8)
	s_waitcnt lgkmcnt(0)
	s_barrier
	s_setprio 1
	s_waitcnt lgkmcnt(0)
	v_mfma_f32_16x16x32_bf16 v[148:151], v[62:65], v[164:167], v[148:151]
	v_mfma_f32_16x16x32_bf16 v[58:61], v[132:135], v[164:167], v[58:61]
	v_mfma_f32_16x16x32_bf16 v[124:127], v[62:65], v[172:175], v[124:127]
	v_mfma_f32_16x16x32_bf16 v[36:39], v[132:135], v[172:175], v[36:39]
	v_mfma_f32_16x16x32_bf16 v[116:119], v[62:65], v[180:183], v[116:119]
	v_mfma_f32_16x16x32_bf16 v[28:31], v[132:135], v[180:183], v[28:31]
	v_mfma_f32_16x16x32_bf16 v[108:111], v[62:65], v[188:191], v[108:111]
	v_mfma_f32_16x16x32_bf16 v[20:23], v[132:135], v[188:191], v[20:23]
	v_mfma_f32_16x16x32_bf16 v[148:151], v[128:131], v[168:171], v[148:151]
	v_mfma_f32_16x16x32_bf16 v[58:61], v[136:139], v[168:171], v[58:61]
	v_mfma_f32_16x16x32_bf16 v[124:127], v[128:131], v[176:179], v[124:127]
	v_mfma_f32_16x16x32_bf16 v[36:39], v[136:139], v[176:179], v[36:39]
	v_mfma_f32_16x16x32_bf16 v[116:119], v[128:131], v[184:187], v[116:119]
	v_mfma_f32_16x16x32_bf16 v[28:31], v[136:139], v[184:187], v[28:31]
	v_mfma_f32_16x16x32_bf16 v[108:111], v[128:131], v[192:195], v[108:111]
	v_mfma_f32_16x16x32_bf16 v[20:23], v[136:139], v[192:195], v[20:23]
	s_setprio 0
	s_setprio 1
	v_mfma_f32_16x16x32_bf16 v[144:147], v[140:143], v[164:167], v[144:147]
	v_mfma_f32_16x16x32_bf16 v[40:43], v[156:159], v[164:167], v[40:43]
	v_mfma_f32_16x16x32_bf16 v[120:123], v[140:143], v[172:175], v[120:123]
	v_mfma_f32_16x16x32_bf16 v[32:35], v[156:159], v[172:175], v[32:35]
	v_mfma_f32_16x16x32_bf16 v[112:115], v[140:143], v[180:183], v[112:115]
	v_mfma_f32_16x16x32_bf16 v[24:27], v[156:159], v[180:183], v[24:27]
	v_mfma_f32_16x16x32_bf16 v[104:107], v[140:143], v[188:191], v[104:107]
	v_mfma_f32_16x16x32_bf16 v[16:19], v[156:159], v[188:191], v[16:19]
	v_mfma_f32_16x16x32_bf16 v[144:147], v[152:155], v[168:171], v[144:147]
	v_mfma_f32_16x16x32_bf16 v[40:43], v[160:163], v[168:171], v[40:43]
	v_mfma_f32_16x16x32_bf16 v[120:123], v[152:155], v[176:179], v[120:123]
	v_mfma_f32_16x16x32_bf16 v[32:35], v[160:163], v[176:179], v[32:35]
	v_mfma_f32_16x16x32_bf16 v[112:115], v[152:155], v[184:187], v[112:115]
	v_mfma_f32_16x16x32_bf16 v[24:27], v[160:163], v[184:187], v[24:27]
	v_mfma_f32_16x16x32_bf16 v[104:107], v[152:155], v[192:195], v[104:107]
	v_mfma_f32_16x16x32_bf16 v[16:19], v[160:163], v[192:195], v[16:19]
	s_setprio 0
	s_barrier
	s_add_i32 s0, s14, s39
	v_lshl_add_u64 v[196:197], s[6:7], 0, v[206:207]
	s_mov_b32 m0, s0
	ds_read_b128 v[164:167], v243 offset:16384
	ds_read_b128 v[168:171], v243 offset:17408
	ds_read_b128 v[172:175], v243 offset:18432
	ds_read_b128 v[176:179], v243 offset:19456
	ds_read_b128 v[180:183], v243 offset:20480
	ds_read_b128 v[184:187], v243 offset:21504
	ds_read_b128 v[188:191], v243 offset:22528
	ds_read_b128 v[192:195], v243 offset:23552
	global_load_lds_dwordx4 v[196:197], off
	s_add_i32 m0, s0, 0x2000
	s_add_u32 s0, s6, 0x80000
	v_lshl_add_u64 v[198:199], s[6:7], 0, v[210:211]
	s_addc_u32 s1, s7, 0
	s_add_i32 s14, s15, s39
	global_load_lds_dwordx4 v[198:199], off
	s_mov_b32 m0, s14
	v_lshl_add_u64 v[216:217], s[8:9], 0, v[204:205]
	global_load_lds_dwordx4 v206, s[0:1]
	v_lshl_add_u64 v[52:53], s[0:1], 0, v[210:211]
	s_add_i32 m0, s14, 0x2000
	v_lshl_add_u64 v[218:219], s[8:9], 0, v[208:209]
	global_load_lds_dwordx4 v[52:53], off
	s_mov_b32 m0, s57
	s_nop 0
	global_load_lds_dwordx4 v[216:217], off
	s_mov_b32 m0, s70
	s_nop 0
	global_load_lds_dwordx4 v[218:219], off
	s_waitcnt vmcnt(8)
	s_waitcnt lgkmcnt(0)
	s_barrier
; #define PG8_STAGE(bufoff, gbase, voff) do { _Pragma("unroll") for (int _i = 0; _i < 2; ++_i) \
;         __builtin_amdgcn_global_load_lds((const unsigned*)((const char*)(gbase) + (voff)[_i]), (LAS unsigned*)(lds + (bufoff) + ldsw + _i * 8192), 16, 0, 0); } while (0)
; #define PG8_LDA(dst, b, h) do { _Pragma("unroll") for (int m = 0; m < 4; ++m) _Pragma("unroll") for (int k = 0; k < 2; ++k) dst[m][k] = *(const LAS bf16x8*)(lds + PG8_SA(b, h) + aoff + m * 2048 + k * 1024); } while (0)
; #define PG8_LDB(dst, b, h) do { _Pragma("unroll") for (int n = 0; n < 2; ++n) _Pragma("unroll") for (int k = 0; k < 2; ++k) dst[n][k] = *(const LAS bf16x8*)(lds + PG8_SB(b, h) + boff + n * 2048 + k * 1024); } while (0)
; #define PG8_MMA(ai, bj, At, Bt) do { __builtin_amdgcn_s_setprio(1); _Pragma("unroll") for (int m = 0; m < 4; ++m) _Pragma("unroll") for (int n = 0; n < 2; ++n) _Pragma("unroll") for (int k = 0; k < 2; ++k) \
;         acc[ai][bj][m][n] = __builtin_amdgcn_mfma_f32_16x16x32_bf16(Bt[n][k], At[m][k], acc[ai][bj][m][n], 0, 0, 0); __builtin_amdgcn_s_setprio(0); } while (0)
; #define PG8_WAIT_V(n) asm volatile("s_waitcnt vmcnt(" #n ")" ::: "memory")
; #define PG8_WAIT_L(n) asm volatile("s_waitcnt lgkmcnt(" #n ")" ::: "memory")
; #define PG8_BAR __builtin_amdgcn_s_barrier()
; #define PG8_SCHED __builtin_amdgcn_sched_barrier(0)
; template <class Epi, class Sched, bool APERM = false, bool HALFN = false>
; __device__ __forceinline__ void gemm_phase(LAS unsigned char* lds, const int tid_in, const int K, const Sched& S, const Epi& E) {
;     ...
;             PG8_WAIT_V(8); PG8_WAIT_L(0); PG8_BAR; PG8_MMA(1, 0, At, B0); if constexpr (!HALFN) PG8_MMA(1, 1, At, B1); PG8_BAR; PG8_SCHED;
;             PG8_LDB(B0, 1, 0); PG8_LDB(B1, 1, 1); PG8_SCHED; PG8_LDA(At, 1, 0); PG8_STAGE(PG8_SA(0, 1), a2 + hstepA, voffA);
;             PG8_WAIT_V(8); PG8_WAIT_L(0); PG8_BAR; PG8_MMA(0, 0, At, B0); if constexpr (!HALFN) PG8_MMA(0, 1, At, B1); PG8_BAR; PG8_SCHED;
	s_setprio 1
	s_waitcnt lgkmcnt(0)
	v_mfma_f32_16x16x32_bf16 v[100:103], v[62:65], v[164:167], v[100:103]
	v_mfma_f32_16x16x32_bf16 v[12:15], v[132:135], v[164:167], v[12:15]
	v_mfma_f32_16x16x32_bf16 v[92:95], v[62:65], v[172:175], v[92:95]
	v_mfma_f32_16x16x32_bf16 v[4:7], v[132:135], v[172:175], v[4:7]
	v_mfma_f32_16x16x32_bf16 v[48:51], v[62:65], v[180:183], v[48:51]
	v_mfma_f32_16x16x32_bf16 v[72:75], v[132:135], v[180:183], v[72:75]
	v_mfma_f32_16x16x32_bf16 v[66:69], v[132:135], v[188:191], v[68:71]
	v_mfma_f32_16x16x32_bf16 v[100:103], v[128:131], v[168:171], v[100:103]
	v_mfma_f32_16x16x32_bf16 v[12:15], v[136:139], v[168:171], v[12:15]
	v_mfma_f32_16x16x32_bf16 v[92:95], v[128:131], v[176:179], v[92:95]
	v_mfma_f32_16x16x32_bf16 v[4:7], v[136:139], v[176:179], v[4:7]
	v_mfma_f32_16x16x32_bf16 v[48:51], v[128:131], v[184:187], v[48:51]
	v_mfma_f32_16x16x32_bf16 v[72:75], v[136:139], v[184:187], v[72:75]
	v_mfma_f32_16x16x32_bf16 v[62:65], v[62:65], v[188:191], v[80:83]
	v_mfma_f32_16x16x32_bf16 v[66:69], v[136:139], v[192:195], v[66:69]
	v_mfma_f32_16x16x32_bf16 v[62:65], v[128:131], v[192:195], v[62:65]
	s_setprio 0
	s_setprio 1
	v_mfma_f32_16x16x32_bf16 v[80:83], v[140:143], v[164:167], v[96:99]
	v_mfma_f32_16x16x32_bf16 v[96:99], v[152:155], v[168:171], v[80:83]
	v_mfma_f32_16x16x32_bf16 v[80:83], v[140:143], v[172:175], v[88:91]
	v_mfma_f32_16x16x32_bf16 v[8:11], v[156:159], v[164:167], v[8:11]
	v_mfma_f32_16x16x32_bf16 v[88:91], v[152:155], v[176:179], v[80:83]
	v_mfma_f32_16x16x32_bf16 v[0:3], v[156:159], v[172:175], v[0:3]
	v_mfma_f32_16x16x32_bf16 v[80:83], v[140:143], v[180:183], v[84:87]
	v_mfma_f32_16x16x32_bf16 v[52:55], v[156:159], v[180:183], v[54:57]
	v_mfma_f32_16x16x32_bf16 v[76:79], v[140:143], v[188:191], v[76:79]
	v_mfma_f32_16x16x32_bf16 v[44:47], v[156:159], v[188:191], v[44:47]
	v_mfma_f32_16x16x32_bf16 v[8:11], v[160:163], v[168:171], v[8:11]
	v_mfma_f32_16x16x32_bf16 v[0:3], v[160:163], v[176:179], v[0:3]
	v_mfma_f32_16x16x32_bf16 v[84:87], v[152:155], v[184:187], v[80:83]
	v_mfma_f32_16x16x32_bf16 v[52:55], v[160:163], v[184:187], v[52:55]
	v_mfma_f32_16x16x32_bf16 v[76:79], v[152:155], v[192:195], v[76:79]
	v_mfma_f32_16x16x32_bf16 v[44:47], v[160:163], v[192:195], v[44:47]
	s_setprio 0
	s_barrier
	s_add_i32 s14, 0, 0x18000
	v_add_u32_e32 v56, s14, v202
	s_add_i32 s15, 0, 0x1c000
	ds_read_b128 v[80:83], v56
	ds_read_b128 v[128:131], v56 offset:1024
	ds_read_b128 v[132:135], v56 offset:2048
	ds_read_b128 v[136:139], v56 offset:3072
	v_add_u32_e32 v56, s15, v202
	ds_read_b128 v[140:143], v56
	ds_read_b128 v[152:155], v56 offset:1024
	ds_read_b128 v[156:159], v56 offset:2048
	ds_read_b128 v[160:163], v56 offset:3072
	s_add_u32 s0, s8, 0x4000
	s_addc_u32 s1, s9, 0
	s_mov_b32 m0, s71
	ds_read_b128 v[164:167], v243 offset:32768
	ds_read_b128 v[168:171], v243 offset:33792
	ds_read_b128 v[172:175], v243 offset:34816
	ds_read_b128 v[176:179], v243 offset:35840
	ds_read_b128 v[180:183], v243 offset:36864
	ds_read_b128 v[184:187], v243 offset:37888
	ds_read_b128 v[188:191], v243 offset:38912
	ds_read_b128 v[192:195], v243 offset:39936
	global_load_lds_dwordx4 v204, s[0:1]
	v_lshl_add_u64 v[56:57], s[0:1], 0, v[208:209]
	s_mov_b32 m0, s72
	s_nop 0
	global_load_lds_dwordx4 v[56:57], off
	s_waitcnt vmcnt(8)
	s_waitcnt lgkmcnt(0)
	s_barrier
	s_setprio 1
	s_waitcnt lgkmcnt(0)
	v_mfma_f32_16x16x32_bf16 v[148:151], v[80:83], v[164:167], v[148:151]
	v_mfma_f32_16x16x32_bf16 v[56:59], v[132:135], v[164:167], v[58:61]
	v_mfma_f32_16x16x32_bf16 v[124:127], v[80:83], v[172:175], v[124:127]
	v_mfma_f32_16x16x32_bf16 v[36:39], v[132:135], v[172:175], v[36:39]
	v_mfma_f32_16x16x32_bf16 v[116:119], v[80:83], v[180:183], v[116:119]
	v_mfma_f32_16x16x32_bf16 v[28:31], v[132:135], v[180:183], v[28:31]
	v_mfma_f32_16x16x32_bf16 v[108:111], v[80:83], v[188:191], v[108:111]
	v_mfma_f32_16x16x32_bf16 v[20:23], v[132:135], v[188:191], v[20:23]
	v_mfma_f32_16x16x32_bf16 v[148:151], v[128:131], v[168:171], v[148:151]
	v_mfma_f32_16x16x32_bf16 v[58:61], v[136:139], v[168:171], v[56:59]
	v_mfma_f32_16x16x32_bf16 v[124:127], v[128:131], v[176:179], v[124:127]
	v_mfma_f32_16x16x32_bf16 v[36:39], v[136:139], v[176:179], v[36:39]
	v_mfma_f32_16x16x32_bf16 v[116:119], v[128:131], v[184:187], v[116:119]
	v_mfma_f32_16x16x32_bf16 v[28:31], v[136:139], v[184:187], v[28:31]
	v_mfma_f32_16x16x32_bf16 v[108:111], v[128:131], v[192:195], v[108:111]
	v_mfma_f32_16x16x32_bf16 v[20:23], v[136:139], v[192:195], v[20:23]
	s_setprio 0
	s_setprio 1
	v_mfma_f32_16x16x32_bf16 v[144:147], v[140:143], v[164:167], v[144:147]
	v_mfma_f32_16x16x32_bf16 v[40:43], v[156:159], v[164:167], v[40:43]
	v_mfma_f32_16x16x32_bf16 v[120:123], v[140:143], v[172:175], v[120:123]
	v_mfma_f32_16x16x32_bf16 v[32:35], v[156:159], v[172:175], v[32:35]
	v_mfma_f32_16x16x32_bf16 v[112:115], v[140:143], v[180:183], v[112:115]
	v_mfma_f32_16x16x32_bf16 v[24:27], v[156:159], v[180:183], v[24:27]
	v_mfma_f32_16x16x32_bf16 v[104:107], v[140:143], v[188:191], v[104:107]
	v_mfma_f32_16x16x32_bf16 v[16:19], v[156:159], v[188:191], v[16:19]
	v_mfma_f32_16x16x32_bf16 v[144:147], v[152:155], v[168:171], v[144:147]
	v_mfma_f32_16x16x32_bf16 v[40:43], v[160:163], v[168:171], v[40:43]
	v_mfma_f32_16x16x32_bf16 v[120:123], v[152:155], v[176:179], v[120:123]
	v_mfma_f32_16x16x32_bf16 v[32:35], v[160:163], v[176:179], v[32:35]
	v_mfma_f32_16x16x32_bf16 v[112:115], v[152:155], v[184:187], v[112:115]
	v_mfma_f32_16x16x32_bf16 v[24:27], v[160:163], v[184:187], v[24:27]
	v_mfma_f32_16x16x32_bf16 v[104:107], v[152:155], v[192:195], v[104:107]
	v_mfma_f32_16x16x32_bf16 v[16:19], v[160:163], v[192:195], v[16:19]
	s_setprio 0
	s_barrier
; #define PG8_STAGE(bufoff, gbase, voff) do { _Pragma("unroll") for (int _i = 0; _i < 2; ++_i) \
;         __builtin_amdgcn_global_load_lds((const unsigned*)((const char*)(gbase) + (voff)[_i]), (LAS unsigned*)(lds + (bufoff) + ldsw + _i * 8192), 16, 0, 0); } while (0)
; #define PG8_LDA(dst, b, h) do { _Pragma("unroll") for (int m = 0; m < 4; ++m) _Pragma("unroll") for (int k = 0; k < 2; ++k) dst[m][k] = *(const LAS bf16x8*)(lds + PG8_SA(b, h) + aoff + m * 2048 + k * 1024); } while (0)
; #define PG8_MMA(ai, bj, At, Bt) do { __builtin_amdgcn_s_setprio(1); _Pragma("unroll") for (int m = 0; m < 4; ++m) _Pragma("unroll") for (int n = 0; n < 2; ++n) _Pragma("unroll") for (int k = 0; k < 2; ++k) \
;         acc[ai][bj][m][n] = __builtin_amdgcn_mfma_f32_16x16x32_bf16(Bt[n][k], At[m][k], acc[ai][bj][m][n], 0, 0, 0); __builtin_amdgcn_s_setprio(0); } while (0)
; #define PG8_WAIT_V(n) asm volatile("s_waitcnt vmcnt(" #n ")" ::: "memory")
; #define PG8_WAIT_L(n) asm volatile("s_waitcnt lgkmcnt(" #n ")" ::: "memory")
; #define PG8_BAR __builtin_amdgcn_s_barrier()
; #define PG8_SCHED __builtin_amdgcn_sched_barrier(0)
; template <class Epi, class Sched, bool APERM = false, bool HALFN = false>
; __device__ __forceinline__ void gemm_phase(LAS unsigned char* lds, const int tid_in, const int K, const Sched& S, const Epi& E) {
;     ...
;             PG8_LDA(At, 1, 1); PG8_STAGE(PG8_SB(1, 0), b3, voffB); PG8_STAGE(PG8_SB(1, 1), b3 + hstep, voffB); PG8_STAGE(PG8_SA(1, 0), a3, voffA);
;             PG8_WAIT_V(8); PG8_WAIT_L(0); PG8_BAR; PG8_MMA(1, 0, At, B0); if constexpr (!HALFN) PG8_MMA(1, 1, At, B1); PG8_BAR; PG8_SCHED;
;         }
;         if (wr == 0) PG8_BAR;
	s_add_i32 s0, s14, s39
	v_lshl_add_u64 v[56:57], v[196:197], 0, s[78:79]
	s_mov_b32 m0, s0
	ds_read_b128 v[164:167], v243 offset:49152
	ds_read_b128 v[168:171], v243 offset:50176
	ds_read_b128 v[172:175], v243 offset:51200
	ds_read_b128 v[176:179], v243 offset:52224
	ds_read_b128 v[180:183], v243 offset:53248
	ds_read_b128 v[184:187], v243 offset:54272
	ds_read_b128 v[188:191], v243 offset:55296
	ds_read_b128 v[192:195], v243 offset:56320
	global_load_lds_dwordx4 v[56:57], off
	s_add_i32 m0, s0, 0x2000
	s_add_u32 s0, s6, 0x80080
	v_lshl_add_u64 v[56:57], v[198:199], 0, s[78:79]
	s_addc_u32 s1, s7, 0
	s_add_i32 s6, s15, s39
	global_load_lds_dwordx4 v[56:57], off
	s_mov_b32 m0, s6
	s_nop 0
	global_load_lds_dwordx4 v206, s[0:1]
	s_add_i32 m0, s6, 0x2000
	s_nop 0
	global_load_lds_dwordx4 v210, s[0:1]
	v_lshl_add_u64 v[56:57], v[216:217], 0, s[78:79]
	s_mov_b32 m0, s81
	s_nop 0
	global_load_lds_dwordx4 v[56:57], off
	v_lshl_add_u64 v[56:57], v[218:219], 0, s[78:79]
	s_mov_b32 m0, s86
	s_nop 0
	global_load_lds_dwordx4 v[56:57], off
	s_waitcnt vmcnt(8)
	s_waitcnt lgkmcnt(0)
	s_barrier
	s_setprio 1
	s_waitcnt lgkmcnt(0)
	v_mfma_f32_16x16x32_bf16 v[62:65], v[80:83], v[188:191], v[62:65]
	v_mfma_f32_16x16x32_bf16 v[100:103], v[80:83], v[164:167], v[100:103]
	v_mfma_f32_16x16x32_bf16 v[12:15], v[132:135], v[164:167], v[12:15]
	v_mfma_f32_16x16x32_bf16 v[92:95], v[80:83], v[172:175], v[92:95]
	v_mfma_f32_16x16x32_bf16 v[4:7], v[132:135], v[172:175], v[4:7]
	v_mfma_f32_16x16x32_bf16 v[48:51], v[80:83], v[180:183], v[48:51]
	v_mfma_f32_16x16x32_bf16 v[70:73], v[132:135], v[180:183], v[72:75]
	v_mfma_f32_16x16x32_bf16 v[80:83], v[128:131], v[192:195], v[62:65]
	v_mfma_f32_16x16x32_bf16 v[62:65], v[132:135], v[188:191], v[66:69]
	v_mfma_f32_16x16x32_bf16 v[100:103], v[128:131], v[168:171], v[100:103]
	v_mfma_f32_16x16x32_bf16 v[12:15], v[136:139], v[168:171], v[12:15]
	v_mfma_f32_16x16x32_bf16 v[92:95], v[128:131], v[176:179], v[92:95]
	v_mfma_f32_16x16x32_bf16 v[4:7], v[136:139], v[176:179], v[4:7]
	v_mfma_f32_16x16x32_bf16 v[48:51], v[128:131], v[184:187], v[48:51]
	v_mfma_f32_16x16x32_bf16 v[72:75], v[136:139], v[184:187], v[70:73]
	v_mfma_f32_16x16x32_bf16 v[68:71], v[136:139], v[192:195], v[62:65]
	s_setprio 0
	s_setprio 1
	v_mfma_f32_16x16x32_bf16 v[62:65], v[140:143], v[164:167], v[96:99]
	v_mfma_f32_16x16x32_bf16 v[96:99], v[152:155], v[168:171], v[62:65]
	v_mfma_f32_16x16x32_bf16 v[62:65], v[140:143], v[172:175], v[88:91]
	v_mfma_f32_16x16x32_bf16 v[88:91], v[152:155], v[176:179], v[62:65]
	v_mfma_f32_16x16x32_bf16 v[62:65], v[140:143], v[180:183], v[84:87]
	v_mfma_f32_16x16x32_bf16 v[8:11], v[156:159], v[164:167], v[8:11]
	v_mfma_f32_16x16x32_bf16 v[0:3], v[156:159], v[172:175], v[0:3]
	v_mfma_f32_16x16x32_bf16 v[84:87], v[152:155], v[184:187], v[62:65]
	v_mfma_f32_16x16x32_bf16 v[52:55], v[156:159], v[180:183], v[52:55]
	v_mfma_f32_16x16x32_bf16 v[62:65], v[140:143], v[188:191], v[76:79]
	v_mfma_f32_16x16x32_bf16 v[44:47], v[156:159], v[188:191], v[44:47]
	v_mfma_f32_16x16x32_bf16 v[8:11], v[160:163], v[168:171], v[8:11]
	v_mfma_f32_16x16x32_bf16 v[0:3], v[160:163], v[176:179], v[0:3]
	v_mfma_f32_16x16x32_bf16 v[54:57], v[160:163], v[184:187], v[52:55]
	v_mfma_f32_16x16x32_bf16 v[76:79], v[152:155], v[192:195], v[62:65]
	v_mfma_f32_16x16x32_bf16 v[44:47], v[160:163], v[192:195], v[44:47]
	s_setprio 0
	s_barrier
	s_add_i32 s13, s13, 2
	s_add_u32 s11, s11, 0x100
	s_addc_u32 s12, s12, 0
	s_cmp_gt_u32 s13, 29
	s_mov_b64 s[0:1], s[4:5]
	s_cbranch_scc0 .LBB0_902
	s_and_b64 vcc, exec, s[16:17]
	s_cbranch_vccz .LBB0_905
	s_barrier
